# accumulator zeroing with 64 v_mov_b64 instead of 128 v_mov_b32 per tile
# speedup vs baseline: 1.0333x; 1.0032x over previous
;     ...
;         const bool has_next = S.next(ui + 1, nxt);
;         const char* nA = has_next ? (const char*)g.A + (size_t)nxt.pm * tstep : cA; const char* nB = has_next ? (const char*)g.Bt + (size_t)nxt.pn * tstep : cB;
;     ...
; #pragma unroll
;         for (int a = 0; a < 2; ++a)
; #pragma unroll
;             for (int b = 0; b < 2; ++b)
; #pragma unroll
;                 for (int m = 0; m < 4; ++m)
; #pragma unroll
;                     for (int n = 0; n < 2; ++n) acc[a][b][m][n] = (f32x4){0.f, 0.f, 0.f, 0.f};
;         cur = nxt; cA = nA; cB = nB; ++ui;
.LBB0_229:
	s_ashr_i32 s73, s72, 31
	s_lshl_b64 s[20:21], s[72:73], 20
	s_add_u32 s74, s54, s20
	s_addc_u32 s75, s55, s21
	s_and_b64 s[20:21], s[4:5], exec
	s_cselect_b32 s15, s75, s81
	s_cselect_b32 s20, s74, s80
	s_ashr_i32 s71, s70, 31
	s_lshl_b64 s[22:23], s[70:71], 20
	s_add_u32 s76, s31, s22
	v_readlane_b32 s12, v255, 48
	s_addc_u32 s77, s12, s23
	s_and_b64 s[22:23], s[4:5], exec
	s_cselect_b32 s21, s77, s83
	s_cselect_b32 s22, s76, s82
	s_add_u32 s80, s80, 0x80080
	s_addc_u32 s81, s81, 0
	s_add_u32 s23, s82, 0x100
	s_addc_u32 s25, s83, 0
	s_mov_b32 s28, -2
	v_mov_b64_e32 v[0:1], 0
	v_mov_b64_e32 v[2:3], 0
	v_mov_b64_e32 v[4:5], 0
	v_mov_b64_e32 v[6:7], 0
	v_mov_b64_e32 v[8:9], 0
	v_mov_b64_e32 v[10:11], 0
	v_mov_b64_e32 v[12:13], 0
	v_mov_b64_e32 v[14:15], 0
	v_mov_b64_e32 v[16:17], 0
	v_mov_b64_e32 v[18:19], 0
	v_mov_b64_e32 v[20:21], 0
	v_mov_b64_e32 v[22:23], 0
	v_mov_b64_e32 v[24:25], 0
	v_mov_b64_e32 v[26:27], 0
	v_mov_b64_e32 v[28:29], 0
	v_mov_b64_e32 v[30:31], 0
	v_mov_b64_e32 v[32:33], 0
	v_mov_b64_e32 v[34:35], 0
	v_mov_b64_e32 v[36:37], 0
	v_mov_b64_e32 v[38:39], 0
	v_mov_b64_e32 v[40:41], 0
	v_mov_b64_e32 v[42:43], 0
	v_mov_b64_e32 v[44:45], 0
	v_mov_b64_e32 v[46:47], 0
	v_mov_b64_e32 v[48:49], 0
	v_mov_b64_e32 v[50:51], 0
	v_mov_b64_e32 v[52:53], 0
	v_mov_b64_e32 v[54:55], 0
	v_mov_b64_e32 v[56:57], 0
	v_mov_b64_e32 v[58:59], 0
	v_mov_b64_e32 v[60:61], 0
	v_mov_b64_e32 v[62:63], 0
	v_mov_b64_e32 v[64:65], 0
	v_mov_b64_e32 v[66:67], 0
	v_mov_b64_e32 v[68:69], 0
	v_mov_b64_e32 v[70:71], 0
	v_mov_b64_e32 v[72:73], 0
	v_mov_b64_e32 v[74:75], 0
	v_mov_b64_e32 v[76:77], 0
	v_mov_b64_e32 v[78:79], 0
	v_mov_b64_e32 v[80:81], 0
	v_mov_b64_e32 v[82:83], 0
	v_mov_b64_e32 v[84:85], 0
	v_mov_b64_e32 v[86:87], 0
	v_mov_b64_e32 v[88:89], 0
	v_mov_b64_e32 v[90:91], 0
	v_mov_b64_e32 v[92:93], 0
	v_mov_b64_e32 v[94:95], 0
	v_mov_b64_e32 v[96:97], 0
	v_mov_b64_e32 v[98:99], 0
	v_mov_b64_e32 v[100:101], 0
	v_mov_b64_e32 v[102:103], 0
	v_mov_b64_e32 v[104:105], 0
	v_mov_b64_e32 v[106:107], 0
	v_mov_b64_e32 v[108:109], 0
	v_mov_b64_e32 v[110:111], 0
	v_mov_b64_e32 v[112:113], 0
	v_mov_b64_e32 v[114:115], 0
	v_mov_b64_e32 v[116:117], 0
	v_mov_b64_e32 v[118:119], 0
	v_mov_b64_e32 v[120:121], 0
	v_mov_b64_e32 v[122:123], 0
	v_mov_b64_e32 v[124:125], 0
	v_mov_b64_e32 v[126:127], 0

;     ...
;             const char* a1 = PG8_KADV(cA, (size_t)(t + 1) * kstep);
;             const char* a2 = last ? nA : PG8_KADV(cA, (size_t)(t + 2) * kstep); const char* b2 = last ? nB : PG8_KADV(cB, (size_t)(t + 2) * kstep);
;             const char* a3 = PG8_KADV(a2, kstep); const char* b3 = PG8_KADV(b2, kstep);
;     ...
; #pragma unroll
;         for (int a = 0; a < 2; ++a)
; #pragma unroll
;             for (int b = 0; b < 2; ++b)
; #pragma unroll
;                 for (int m = 0; m < 4; ++m)
; #pragma unroll
;                     for (int n = 0; n < 2; ++n) acc[a][b][m][n] = (f32x4){0.f, 0.f, 0.f, 0.f};
;         cur = nxt; cA = nA; cB = nB; ++ui;
.LBB0_312:
	s_add_u32 s2, s78, 0xffffff00
	s_addc_u32 s30, s79, -1
	s_mov_b32 s3, -2
	v_mov_b64_e32 v[0:1], 0
	v_mov_b64_e32 v[2:3], 0
	v_mov_b64_e32 v[4:5], 0
	v_mov_b64_e32 v[6:7], 0
	v_mov_b64_e32 v[8:9], 0
	v_mov_b64_e32 v[10:11], 0
	v_mov_b64_e32 v[12:13], 0
	v_mov_b64_e32 v[14:15], 0
	v_mov_b64_e32 v[16:17], 0
	v_mov_b64_e32 v[18:19], 0
	v_mov_b64_e32 v[20:21], 0
	v_mov_b64_e32 v[22:23], 0
	v_mov_b64_e32 v[24:25], 0
	v_mov_b64_e32 v[26:27], 0
	v_mov_b64_e32 v[28:29], 0
	v_mov_b64_e32 v[30:31], 0
	v_mov_b64_e32 v[32:33], 0
	v_mov_b64_e32 v[34:35], 0
	v_mov_b64_e32 v[36:37], 0
	v_mov_b64_e32 v[38:39], 0
	v_mov_b64_e32 v[40:41], 0
	v_mov_b64_e32 v[42:43], 0
	v_mov_b64_e32 v[44:45], 0
	v_mov_b64_e32 v[46:47], 0
	v_mov_b64_e32 v[48:49], 0
	v_mov_b64_e32 v[50:51], 0
	v_mov_b64_e32 v[52:53], 0
	v_mov_b64_e32 v[54:55], 0
	v_mov_b64_e32 v[56:57], 0
	v_mov_b64_e32 v[58:59], 0
	v_mov_b64_e32 v[60:61], 0
	v_mov_b64_e32 v[62:63], 0
	v_mov_b64_e32 v[64:65], 0
	v_mov_b64_e32 v[66:67], 0
	v_mov_b64_e32 v[68:69], 0
	v_mov_b64_e32 v[70:71], 0
	v_mov_b64_e32 v[72:73], 0
	v_mov_b64_e32 v[74:75], 0
	v_mov_b64_e32 v[76:77], 0
	v_mov_b64_e32 v[78:79], 0
	v_mov_b64_e32 v[80:81], 0
	v_mov_b64_e32 v[82:83], 0
	v_mov_b64_e32 v[84:85], 0
	v_mov_b64_e32 v[86:87], 0
	v_mov_b64_e32 v[88:89], 0
	v_mov_b64_e32 v[90:91], 0
	v_mov_b64_e32 v[92:93], 0
	v_mov_b64_e32 v[94:95], 0
	v_mov_b64_e32 v[96:97], 0
	v_mov_b64_e32 v[98:99], 0
	v_mov_b64_e32 v[100:101], 0
	v_mov_b64_e32 v[102:103], 0
	v_mov_b64_e32 v[104:105], 0
	v_mov_b64_e32 v[106:107], 0
	v_mov_b64_e32 v[108:109], 0
	v_mov_b64_e32 v[110:111], 0
	v_mov_b64_e32 v[112:113], 0
	v_mov_b64_e32 v[114:115], 0
	v_mov_b64_e32 v[116:117], 0
	v_mov_b64_e32 v[118:119], 0
	v_mov_b64_e32 v[120:121], 0
	v_mov_b64_e32 v[122:123], 0
	v_mov_b64_e32 v[124:125], 0
	v_mov_b64_e32 v[126:127], 0

;     ...
;             const char* a1 = PG8_KADV(cA, (size_t)(t + 1) * kstep);
;             const char* a2 = last ? nA : PG8_KADV(cA, (size_t)(t + 2) * kstep); const char* b2 = last ? nB : PG8_KADV(cB, (size_t)(t + 2) * kstep);
;             const char* a3 = PG8_KADV(a2, kstep); const char* b3 = PG8_KADV(b2, kstep);
;     ...
; #pragma unroll
;         for (int a = 0; a < 2; ++a)
; #pragma unroll
;             for (int b = 0; b < 2; ++b)
; #pragma unroll
;                 for (int m = 0; m < 4; ++m)
; #pragma unroll
;                     for (int n = 0; n < 2; ++n) acc[a][b][m][n] = (f32x4){0.f, 0.f, 0.f, 0.f};
;         cur = nxt; cA = nA; cB = nB; ++ui;
.LBB0_342:
	s_add_u32 s2, s78, 0xffffff00
	v_mov_b64_e32 v[176:177], 0x200
	v_mov_b64_e32 v[228:229], 0xaff
	s_addc_u32 s30, s79, -1
	s_mov_b32 s3, -2
	v_mov_b64_e32 v[0:1], 0
	v_mov_b64_e32 v[2:3], 0
	v_mov_b64_e32 v[4:5], 0
	v_mov_b64_e32 v[6:7], 0
	v_mov_b64_e32 v[8:9], 0
	v_mov_b64_e32 v[10:11], 0
	v_mov_b64_e32 v[12:13], 0
	v_mov_b64_e32 v[14:15], 0
	v_mov_b64_e32 v[16:17], 0
	v_mov_b64_e32 v[18:19], 0
	v_mov_b64_e32 v[20:21], 0
	v_mov_b64_e32 v[22:23], 0
	v_mov_b64_e32 v[24:25], 0
	v_mov_b64_e32 v[26:27], 0
	v_mov_b64_e32 v[28:29], 0
	v_mov_b64_e32 v[30:31], 0
	v_mov_b64_e32 v[32:33], 0
	v_mov_b64_e32 v[34:35], 0
	v_mov_b64_e32 v[36:37], 0
	v_mov_b64_e32 v[38:39], 0
	v_mov_b64_e32 v[40:41], 0
	v_mov_b64_e32 v[42:43], 0
	v_mov_b64_e32 v[44:45], 0
	v_mov_b64_e32 v[46:47], 0
	v_mov_b64_e32 v[48:49], 0
	v_mov_b64_e32 v[50:51], 0
	v_mov_b64_e32 v[52:53], 0
	v_mov_b64_e32 v[54:55], 0
	v_mov_b64_e32 v[56:57], 0
	v_mov_b64_e32 v[58:59], 0
	v_mov_b64_e32 v[60:61], 0
	v_mov_b64_e32 v[62:63], 0
	v_mov_b64_e32 v[64:65], 0
	v_mov_b64_e32 v[66:67], 0
	v_mov_b64_e32 v[68:69], 0
	v_mov_b64_e32 v[70:71], 0
	v_mov_b64_e32 v[72:73], 0
	v_mov_b64_e32 v[74:75], 0
	v_mov_b64_e32 v[76:77], 0
	v_mov_b64_e32 v[78:79], 0
	v_mov_b64_e32 v[80:81], 0
	v_mov_b64_e32 v[82:83], 0
	v_mov_b64_e32 v[84:85], 0
	v_mov_b64_e32 v[86:87], 0
	v_mov_b64_e32 v[88:89], 0
	v_mov_b64_e32 v[90:91], 0
	v_mov_b64_e32 v[92:93], 0
	v_mov_b64_e32 v[94:95], 0
	v_mov_b64_e32 v[96:97], 0
	v_mov_b64_e32 v[98:99], 0
	v_mov_b64_e32 v[100:101], 0
	v_mov_b64_e32 v[102:103], 0
	v_mov_b64_e32 v[104:105], 0
	v_mov_b64_e32 v[106:107], 0
	v_mov_b64_e32 v[108:109], 0
	v_mov_b64_e32 v[110:111], 0
	v_mov_b64_e32 v[112:113], 0
	v_mov_b64_e32 v[114:115], 0
	v_mov_b64_e32 v[116:117], 0
	v_mov_b64_e32 v[118:119], 0
	v_mov_b64_e32 v[120:121], 0
	v_mov_b64_e32 v[122:123], 0
	v_mov_b64_e32 v[124:125], 0
	v_mov_b64_e32 v[126:127], 0

;     ...
;         const bool has_next = S.next(ui + 1, nxt);
;         const char* nA = has_next ? (const char*)g.A + (size_t)nxt.pm * tstep : cA; const char* nB = has_next ? (const char*)g.Bt + (size_t)nxt.pn * tstep : cB;
;     ...
; #pragma unroll
;         for (int a = 0; a < 2; ++a)
; #pragma unroll
;             for (int b = 0; b < 2; ++b)
; #pragma unroll
;                 for (int m = 0; m < 4; ++m)
; #pragma unroll
;                     for (int n = 0; n < 2; ++n) acc[a][b][m][n] = (f32x4){0.f, 0.f, 0.f, 0.f};
;         cur = nxt; cA = nA; cB = nB; ++ui;
.LBB0_489:
	s_ashr_i32 s81, s80, 31
	s_lshl_b64 s[2:3], s[80:81], 20
	s_add_u32 s82, s0, s2
	s_addc_u32 s83, s1, s3
	s_and_b64 s[2:3], s[4:5], exec
	s_cselect_b32 s23, s83, s87
	s_cselect_b32 s25, s82, s86
	s_ashr_i32 s79, s78, 31
	s_lshl_b64 s[2:3], s[78:79], 20
	s_add_u32 s84, s70, s2
	s_addc_u32 s85, s71, s3
	s_and_b64 s[2:3], s[4:5], exec
	s_cselect_b32 s28, s85, s89
	s_cselect_b32 s30, s84, s88
	s_add_u32 s86, s86, 0x80080
	s_addc_u32 s87, s87, 0
	s_add_u32 s33, s88, 0x100
	s_addc_u32 s40, s89, 0
	s_mov_b32 s2, -2
	v_mov_b64_e32 v[0:1], 0
	v_mov_b64_e32 v[2:3], 0
	v_mov_b64_e32 v[4:5], 0
	v_mov_b64_e32 v[6:7], 0
	v_mov_b64_e32 v[8:9], 0
	v_mov_b64_e32 v[10:11], 0
	v_mov_b64_e32 v[12:13], 0
	v_mov_b64_e32 v[14:15], 0
	v_mov_b64_e32 v[16:17], 0
	v_mov_b64_e32 v[18:19], 0
	v_mov_b64_e32 v[20:21], 0
	v_mov_b64_e32 v[22:23], 0
	v_mov_b64_e32 v[24:25], 0
	v_mov_b64_e32 v[26:27], 0
	v_mov_b64_e32 v[28:29], 0
	v_mov_b64_e32 v[30:31], 0
	v_mov_b64_e32 v[32:33], 0
	v_mov_b64_e32 v[34:35], 0
	v_mov_b64_e32 v[36:37], 0
	v_mov_b64_e32 v[38:39], 0
	v_mov_b64_e32 v[40:41], 0
	v_mov_b64_e32 v[42:43], 0
	v_mov_b64_e32 v[44:45], 0
	v_mov_b64_e32 v[46:47], 0
	v_mov_b64_e32 v[48:49], 0
	v_mov_b64_e32 v[50:51], 0
	v_mov_b64_e32 v[52:53], 0
	v_mov_b64_e32 v[54:55], 0
	v_mov_b64_e32 v[56:57], 0
	v_mov_b64_e32 v[58:59], 0
	v_mov_b64_e32 v[60:61], 0
	v_mov_b64_e32 v[62:63], 0
	v_mov_b64_e32 v[64:65], 0
	v_mov_b64_e32 v[66:67], 0
	v_mov_b64_e32 v[68:69], 0
	v_mov_b64_e32 v[70:71], 0
	v_mov_b64_e32 v[72:73], 0
	v_mov_b64_e32 v[74:75], 0
	v_mov_b64_e32 v[76:77], 0
	v_mov_b64_e32 v[78:79], 0
	v_mov_b64_e32 v[80:81], 0
	v_mov_b64_e32 v[82:83], 0
	v_mov_b64_e32 v[84:85], 0
	v_mov_b64_e32 v[86:87], 0
	v_mov_b64_e32 v[88:89], 0
	v_mov_b64_e32 v[90:91], 0
	v_mov_b64_e32 v[92:93], 0
	v_mov_b64_e32 v[94:95], 0
	v_mov_b64_e32 v[96:97], 0
	v_mov_b64_e32 v[98:99], 0
	v_mov_b64_e32 v[100:101], 0
	v_mov_b64_e32 v[102:103], 0
	v_mov_b64_e32 v[104:105], 0
	v_mov_b64_e32 v[106:107], 0
	v_mov_b64_e32 v[108:109], 0
	v_mov_b64_e32 v[110:111], 0
	v_mov_b64_e32 v[112:113], 0
	v_mov_b64_e32 v[114:115], 0
	v_mov_b64_e32 v[116:117], 0
	v_mov_b64_e32 v[118:119], 0
	v_mov_b64_e32 v[120:121], 0
	v_mov_b64_e32 v[122:123], 0
	v_mov_b64_e32 v[124:125], 0
	v_mov_b64_e32 v[126:127], 0

;     ...
;         const bool has_next = S.next(ui + 1, nxt);
;         const char* nA = has_next ? (const char*)g.A + (size_t)nxt.pm * tstep : cA; const char* nB = has_next ? (const char*)g.Bt + (size_t)nxt.pn * tstep : cB;
;     ...
; #pragma unroll
;         for (int a = 0; a < 2; ++a)
; #pragma unroll
;             for (int b = 0; b < 2; ++b)
; #pragma unroll
;                 for (int m = 0; m < 4; ++m)
; #pragma unroll
;                     for (int n = 0; n < 2; ++n) acc[a][b][m][n] = (f32x4){0.f, 0.f, 0.f, 0.f};
;         cur = nxt; cA = nA; cB = nB; ++ui;
.LBB0_513:
	s_ashr_i32 s81, s80, 31
	s_lshl_b64 s[2:3], s[80:81], 20
	s_add_u32 s82, s8, s2
	s_addc_u32 s83, s9, s3
	s_and_b64 s[2:3], s[4:5], exec
	s_cselect_b32 s28, s83, s87
	s_cselect_b32 s30, s82, s86
	s_ashr_i32 s79, s78, 31
	s_lshl_b64 s[2:3], s[78:79], 20
	s_add_u32 s84, s68, s2
	s_addc_u32 s85, s69, s3
	s_and_b64 s[2:3], s[4:5], exec
	s_cselect_b32 s33, s85, s89
	s_cselect_b32 s40, s84, s88
	s_add_u32 s86, s86, 0x80080
	s_addc_u32 s87, s87, 0
	s_add_u32 s42, s88, 0x100
	s_addc_u32 s43, s89, 0
	s_mov_b32 s2, -2
	v_mov_b64_e32 v[0:1], 0
	v_mov_b64_e32 v[2:3], 0
	v_mov_b64_e32 v[4:5], 0
	v_mov_b64_e32 v[6:7], 0
	v_mov_b64_e32 v[8:9], 0
	v_mov_b64_e32 v[10:11], 0
	v_mov_b64_e32 v[12:13], 0
	v_mov_b64_e32 v[14:15], 0
	v_mov_b64_e32 v[16:17], 0
	v_mov_b64_e32 v[18:19], 0
	v_mov_b64_e32 v[20:21], 0
	v_mov_b64_e32 v[22:23], 0
	v_mov_b64_e32 v[24:25], 0
	v_mov_b64_e32 v[26:27], 0
	v_mov_b64_e32 v[28:29], 0
	v_mov_b64_e32 v[30:31], 0
	v_mov_b64_e32 v[32:33], 0
	v_mov_b64_e32 v[34:35], 0
	v_mov_b64_e32 v[36:37], 0
	v_mov_b64_e32 v[38:39], 0
	v_mov_b64_e32 v[40:41], 0
	v_mov_b64_e32 v[42:43], 0
	v_mov_b64_e32 v[44:45], 0
	v_mov_b64_e32 v[46:47], 0
	v_mov_b64_e32 v[48:49], 0
	v_mov_b64_e32 v[50:51], 0
	v_mov_b64_e32 v[52:53], 0
	v_mov_b64_e32 v[54:55], 0
	v_mov_b64_e32 v[56:57], 0
	v_mov_b64_e32 v[58:59], 0
	v_mov_b64_e32 v[60:61], 0
	v_mov_b64_e32 v[62:63], 0
	v_mov_b64_e32 v[64:65], 0
	v_mov_b64_e32 v[66:67], 0
	v_mov_b64_e32 v[68:69], 0
	v_mov_b64_e32 v[70:71], 0
	v_mov_b64_e32 v[72:73], 0
	v_mov_b64_e32 v[74:75], 0
	v_mov_b64_e32 v[76:77], 0
	v_mov_b64_e32 v[78:79], 0
	v_mov_b64_e32 v[80:81], 0
	v_mov_b64_e32 v[82:83], 0
	v_mov_b64_e32 v[84:85], 0
	v_mov_b64_e32 v[86:87], 0
	v_mov_b64_e32 v[88:89], 0
	v_mov_b64_e32 v[90:91], 0
	v_mov_b64_e32 v[92:93], 0
	v_mov_b64_e32 v[94:95], 0
	v_mov_b64_e32 v[96:97], 0
	v_mov_b64_e32 v[98:99], 0
	v_mov_b64_e32 v[100:101], 0
	v_mov_b64_e32 v[102:103], 0
	v_mov_b64_e32 v[104:105], 0
	v_mov_b64_e32 v[106:107], 0
	v_mov_b64_e32 v[108:109], 0
	v_mov_b64_e32 v[110:111], 0
	v_mov_b64_e32 v[112:113], 0
	v_mov_b64_e32 v[114:115], 0
	v_mov_b64_e32 v[116:117], 0
	v_mov_b64_e32 v[118:119], 0
	v_mov_b64_e32 v[120:121], 0
	v_mov_b64_e32 v[122:123], 0
	v_mov_b64_e32 v[124:125], 0
	v_mov_b64_e32 v[126:127], 0

;     ...
;         const bool has_next = S.next(ui + 1, nxt);
;         const char* nA = has_next ? (const char*)g.A + (size_t)nxt.pm * tstep : cA; const char* nB = has_next ? (const char*)g.Bt + (size_t)nxt.pn * tstep : cB;
;     ...
; #pragma unroll
;         for (int a = 0; a < 2; ++a)
; #pragma unroll
;             for (int b = 0; b < 2; ++b)
; #pragma unroll
;                 for (int m = 0; m < 4; ++m)
; #pragma unroll
;                     for (int n = 0; n < 2; ++n) acc[a][b][m][n] = (f32x4){0.f, 0.f, 0.f, 0.f};
;         cur = nxt; cA = nA; cB = nB; ++ui;
.LBB0_540:
	s_ashr_i32 s81, s80, 31
	s_lshl_b64 s[2:3], s[80:81], 20
	s_add_u32 s82, s54, s2
	s_addc_u32 s83, s55, s3
	s_and_b64 s[2:3], s[4:5], exec
	s_cselect_b32 s15, s83, s89
	s_cselect_b32 s30, s82, s88
	s_ashr_i32 s79, s78, 31
	s_lshl_b64 s[2:3], s[78:79], 20
	s_add_u32 s84, s10, s2
	s_addc_u32 s85, s19, s3
	s_and_b64 s[2:3], s[4:5], exec
	s_cselect_b32 s33, s85, s91
	s_cselect_b32 s40, s84, s90
	s_add_u32 s88, s88, 0x80080
	s_addc_u32 s89, s89, 0
	s_add_u32 s42, s90, 0x100
	s_addc_u32 s43, s91, 0
	s_mov_b32 s2, -2
	v_mov_b64_e32 v[0:1], 0
	v_mov_b64_e32 v[2:3], 0
	v_mov_b64_e32 v[4:5], 0
	v_mov_b64_e32 v[6:7], 0
	v_mov_b64_e32 v[8:9], 0
	v_mov_b64_e32 v[10:11], 0
	v_mov_b64_e32 v[12:13], 0
	v_mov_b64_e32 v[14:15], 0
	v_mov_b64_e32 v[16:17], 0
	v_mov_b64_e32 v[18:19], 0
	v_mov_b64_e32 v[20:21], 0
	v_mov_b64_e32 v[22:23], 0
	v_mov_b64_e32 v[24:25], 0
	v_mov_b64_e32 v[26:27], 0
	v_mov_b64_e32 v[28:29], 0
	v_mov_b64_e32 v[30:31], 0
	v_mov_b64_e32 v[32:33], 0
	v_mov_b64_e32 v[34:35], 0
	v_mov_b64_e32 v[36:37], 0
	v_mov_b64_e32 v[38:39], 0
	v_mov_b64_e32 v[40:41], 0
	v_mov_b64_e32 v[42:43], 0
	v_mov_b64_e32 v[44:45], 0
	v_mov_b64_e32 v[46:47], 0
	v_mov_b64_e32 v[48:49], 0
	v_mov_b64_e32 v[50:51], 0
	v_mov_b64_e32 v[52:53], 0
	v_mov_b64_e32 v[54:55], 0
	v_mov_b64_e32 v[56:57], 0
	v_mov_b64_e32 v[58:59], 0
	v_mov_b64_e32 v[60:61], 0
	v_mov_b64_e32 v[62:63], 0
	v_mov_b64_e32 v[64:65], 0
	v_mov_b64_e32 v[66:67], 0
	v_mov_b64_e32 v[68:69], 0
	v_mov_b64_e32 v[70:71], 0
	v_mov_b64_e32 v[72:73], 0
	v_mov_b64_e32 v[74:75], 0
	v_mov_b64_e32 v[76:77], 0
	v_mov_b64_e32 v[78:79], 0
	v_mov_b64_e32 v[80:81], 0
	v_mov_b64_e32 v[82:83], 0
	v_mov_b64_e32 v[84:85], 0
	v_mov_b64_e32 v[86:87], 0
	v_mov_b64_e32 v[88:89], 0
	v_mov_b64_e32 v[90:91], 0
	v_mov_b64_e32 v[92:93], 0
	v_mov_b64_e32 v[94:95], 0
	v_mov_b64_e32 v[96:97], 0
	v_mov_b64_e32 v[98:99], 0
	v_mov_b64_e32 v[100:101], 0
	v_mov_b64_e32 v[102:103], 0
	v_mov_b64_e32 v[104:105], 0
	v_mov_b64_e32 v[106:107], 0
	v_mov_b64_e32 v[108:109], 0
	v_mov_b64_e32 v[110:111], 0
	v_mov_b64_e32 v[112:113], 0
	v_mov_b64_e32 v[114:115], 0
	v_mov_b64_e32 v[116:117], 0
	v_mov_b64_e32 v[118:119], 0
	v_mov_b64_e32 v[120:121], 0
	v_mov_b64_e32 v[122:123], 0
	v_mov_b64_e32 v[124:125], 0
	v_mov_b64_e32 v[126:127], 0

;     ...
;         const bool has_next = S.next(ui + 1, nxt);
;         const char* nA = has_next ? (const char*)g.A + (size_t)nxt.pm * tstep : cA; const char* nB = has_next ? (const char*)g.Bt + (size_t)nxt.pn * tstep : cB;
;     ...
; #pragma unroll
;         for (int a = 0; a < 2; ++a)
; #pragma unroll
;             for (int b = 0; b < 2; ++b)
; #pragma unroll
;                 for (int m = 0; m < 4; ++m)
; #pragma unroll
;                     for (int n = 0; n < 2; ++n) acc[a][b][m][n] = (f32x4){0.f, 0.f, 0.f, 0.f};
;         cur = nxt; cA = nA; cB = nB; ++ui;
.LBB0_625:
	s_ashr_i32 s81, s80, 31
	s_lshl_b64 s[2:3], s[80:81], 19
	s_add_u32 s82, s23, s2
	s_addc_u32 s83, s28, s3
	s_and_b64 s[2:3], s[76:77], exec
	s_cselect_b32 s75, s83, s87
	s_cselect_b32 s81, s82, s86
	s_ashr_i32 s79, s78, 31
	s_lshl_b64 s[2:3], s[78:79], 19
	s_add_u32 s84, s57, s2
	s_addc_u32 s85, s59, s3
	s_and_b64 s[2:3], s[76:77], exec
	s_cselect_b32 s79, s85, s89
	s_cselect_b32 vcc_lo, s84, s88
	s_add_u32 s86, s86, 0x40080
	s_addc_u32 s87, s87, 0
	s_add_u32 vcc_hi, s88, 0x100
	s_addc_u32 s2, s89, 0
	s_mov_b32 s3, -2
	v_mov_b64_e32 v[0:1], 0
	v_mov_b64_e32 v[2:3], 0
	v_mov_b64_e32 v[4:5], 0
	v_mov_b64_e32 v[6:7], 0
	v_mov_b64_e32 v[8:9], 0
	v_mov_b64_e32 v[10:11], 0
	v_mov_b64_e32 v[12:13], 0
	v_mov_b64_e32 v[14:15], 0
	v_mov_b64_e32 v[16:17], 0
	v_mov_b64_e32 v[18:19], 0
	v_mov_b64_e32 v[20:21], 0
	v_mov_b64_e32 v[22:23], 0
	v_mov_b64_e32 v[24:25], 0
	v_mov_b64_e32 v[26:27], 0
	v_mov_b64_e32 v[28:29], 0
	v_mov_b64_e32 v[30:31], 0
	v_mov_b64_e32 v[32:33], 0
	v_mov_b64_e32 v[34:35], 0
	v_mov_b64_e32 v[36:37], 0
	v_mov_b64_e32 v[38:39], 0
	v_mov_b64_e32 v[40:41], 0
	v_mov_b64_e32 v[42:43], 0
	v_mov_b64_e32 v[44:45], 0
	v_mov_b64_e32 v[46:47], 0
	v_mov_b64_e32 v[48:49], 0
	v_mov_b64_e32 v[50:51], 0
	v_mov_b64_e32 v[52:53], 0
	v_mov_b64_e32 v[54:55], 0
	v_mov_b64_e32 v[56:57], 0
	v_mov_b64_e32 v[58:59], 0
	v_mov_b64_e32 v[60:61], 0
	v_mov_b64_e32 v[62:63], 0
	v_mov_b64_e32 v[64:65], 0
	v_mov_b64_e32 v[66:67], 0
	v_mov_b64_e32 v[68:69], 0
	v_mov_b64_e32 v[70:71], 0
	v_mov_b64_e32 v[72:73], 0
	v_mov_b64_e32 v[74:75], 0
	v_mov_b64_e32 v[76:77], 0
	v_mov_b64_e32 v[78:79], 0
	v_mov_b64_e32 v[80:81], 0
	v_mov_b64_e32 v[82:83], 0
	v_mov_b64_e32 v[84:85], 0
	v_mov_b64_e32 v[86:87], 0
	v_mov_b64_e32 v[88:89], 0
	v_mov_b64_e32 v[90:91], 0
	v_mov_b64_e32 v[92:93], 0
	v_mov_b64_e32 v[94:95], 0
	v_mov_b64_e32 v[96:97], 0
	v_mov_b64_e32 v[98:99], 0
	v_mov_b64_e32 v[100:101], 0
	v_mov_b64_e32 v[102:103], 0
	v_mov_b64_e32 v[104:105], 0
	v_mov_b64_e32 v[106:107], 0
	v_mov_b64_e32 v[108:109], 0
	v_mov_b64_e32 v[110:111], 0
	v_mov_b64_e32 v[112:113], 0
	v_mov_b64_e32 v[114:115], 0
	v_mov_b64_e32 v[116:117], 0
	v_mov_b64_e32 v[118:119], 0
	v_mov_b64_e32 v[120:121], 0
	v_mov_b64_e32 v[122:123], 0
	v_mov_b64_e32 v[124:125], 0
	v_mov_b64_e32 v[126:127], 0

;     ...
;         const bool has_next = S.next(ui + 1, nxt);
;         const char* nA = has_next ? (const char*)g.A + (size_t)nxt.pm * tstep : cA; const char* nB = has_next ? (const char*)g.Bt + (size_t)nxt.pn * tstep : cB;
;     ...
; #pragma unroll
;         for (int a = 0; a < 2; ++a)
; #pragma unroll
;             for (int b = 0; b < 2; ++b)
; #pragma unroll
;                 for (int m = 0; m < 4; ++m)
; #pragma unroll
;                     for (int n = 0; n < 2; ++n) acc[a][b][m][n] = (f32x4){0.f, 0.f, 0.f, 0.f};
;         cur = nxt; cA = nA; cB = nB; ++ui;
.LBB0_855:
	s_ashr_i32 s75, s74, 31
	s_lshl_b64 s[2:3], s[74:75], 20
	s_add_u32 s76, s68, s2
	s_addc_u32 s77, s69, s3
	s_and_b64 s[2:3], s[4:5], exec
	s_cselect_b32 s15, s77, s83
	s_cselect_b32 s23, s76, s82
	s_ashr_i32 s73, s72, 31
	s_lshl_b64 s[2:3], s[72:73], 20
	s_add_u32 s78, s0, s2
	s_addc_u32 s79, s1, s3
	s_and_b64 s[2:3], s[4:5], exec
	s_cselect_b32 s25, s79, s85
	s_cselect_b32 s28, s78, s84
	s_add_u32 s82, s82, 0x80080
	s_addc_u32 s83, s83, 0
	s_add_u32 s30, s84, 0x100
	s_addc_u32 s2, s85, 0
	s_mov_b32 s3, -2
	v_mov_b64_e32 v[0:1], 0
	v_mov_b64_e32 v[2:3], 0
	v_mov_b64_e32 v[4:5], 0
	v_mov_b64_e32 v[6:7], 0
	v_mov_b64_e32 v[8:9], 0
	v_mov_b64_e32 v[10:11], 0
	v_mov_b64_e32 v[12:13], 0
	v_mov_b64_e32 v[14:15], 0
	v_mov_b64_e32 v[16:17], 0
	v_mov_b64_e32 v[18:19], 0
	v_mov_b64_e32 v[20:21], 0
	v_mov_b64_e32 v[22:23], 0
	v_mov_b64_e32 v[24:25], 0
	v_mov_b64_e32 v[26:27], 0
	v_mov_b64_e32 v[28:29], 0
	v_mov_b64_e32 v[30:31], 0
	v_mov_b64_e32 v[32:33], 0
	v_mov_b64_e32 v[34:35], 0
	v_mov_b64_e32 v[36:37], 0
	v_mov_b64_e32 v[38:39], 0
	v_mov_b64_e32 v[40:41], 0
	v_mov_b64_e32 v[42:43], 0
	v_mov_b64_e32 v[44:45], 0
	v_mov_b64_e32 v[46:47], 0
	v_mov_b64_e32 v[48:49], 0
	v_mov_b64_e32 v[50:51], 0
	v_mov_b64_e32 v[52:53], 0
	v_mov_b64_e32 v[54:55], 0
	v_mov_b64_e32 v[56:57], 0
	v_mov_b64_e32 v[58:59], 0
	v_mov_b64_e32 v[60:61], 0
	v_mov_b64_e32 v[62:63], 0
	v_mov_b64_e32 v[64:65], 0
	v_mov_b64_e32 v[66:67], 0
	v_mov_b64_e32 v[68:69], 0
	v_mov_b64_e32 v[70:71], 0
	v_mov_b64_e32 v[72:73], 0
	v_mov_b64_e32 v[74:75], 0
	v_mov_b64_e32 v[76:77], 0
	v_mov_b64_e32 v[78:79], 0
	v_mov_b64_e32 v[80:81], 0
	v_mov_b64_e32 v[82:83], 0
	v_mov_b64_e32 v[84:85], 0
	v_mov_b64_e32 v[86:87], 0
	v_mov_b64_e32 v[88:89], 0
	v_mov_b64_e32 v[90:91], 0
	v_mov_b64_e32 v[92:93], 0
	v_mov_b64_e32 v[94:95], 0
	v_mov_b64_e32 v[96:97], 0
	v_mov_b64_e32 v[98:99], 0
	v_mov_b64_e32 v[100:101], 0
	v_mov_b64_e32 v[102:103], 0
	v_mov_b64_e32 v[104:105], 0
	v_mov_b64_e32 v[106:107], 0
	v_mov_b64_e32 v[108:109], 0
	v_mov_b64_e32 v[110:111], 0
	v_mov_b64_e32 v[112:113], 0
	v_mov_b64_e32 v[114:115], 0
	v_mov_b64_e32 v[116:117], 0
	v_mov_b64_e32 v[118:119], 0
	v_mov_b64_e32 v[120:121], 0
	v_mov_b64_e32 v[122:123], 0
	v_mov_b64_e32 v[124:125], 0
	v_mov_b64_e32 v[126:127], 0

;     ...
;         const bool has_next = S.next(ui + 1, nxt);
;         const char* nA = has_next ? (const char*)g.A + (size_t)nxt.pm * tstep : cA; const char* nB = has_next ? (const char*)g.Bt + (size_t)nxt.pn * tstep : cB;
;     ...
; #pragma unroll
;         for (int a = 0; a < 2; ++a)
; #pragma unroll
;             for (int b = 0; b < 2; ++b)
; #pragma unroll
;                 for (int m = 0; m < 4; ++m)
; #pragma unroll
;                     for (int n = 0; n < 2; ++n) acc[a][b][m][n] = (f32x4){0.f, 0.f, 0.f, 0.f};
;         cur = nxt; cA = nA; cB = nB; ++ui;
.LBB0_982:
	s_ashr_i32 s61, s60, 31
	s_lshl_b64 s[2:3], s[60:61], 20
	s_add_u32 s62, s54, s2
	s_addc_u32 s63, s55, s3
	s_and_b64 s[2:3], s[0:1], exec
	s_cselect_b32 s15, s63, s71
	s_cselect_b32 s28, s62, s70
	s_ashr_i32 s59, s58, 31
	s_lshl_b64 s[2:3], s[58:59], 20
	s_add_u32 s66, s8, s2
	s_addc_u32 s67, s9, s3
	s_and_b64 s[2:3], s[0:1], exec
	s_cselect_b32 s30, s67, s73
	s_cselect_b32 s33, s66, s72
	s_add_u32 s70, s70, 0x80080
	s_addc_u32 s71, s71, 0
	s_add_u32 s40, s72, 0x100
	s_addc_u32 s2, s73, 0
	s_mov_b32 s3, -2
	v_mov_b64_e32 v[0:1], 0
	v_mov_b64_e32 v[2:3], 0
	v_mov_b64_e32 v[4:5], 0
	v_mov_b64_e32 v[6:7], 0
	v_mov_b64_e32 v[8:9], 0
	v_mov_b64_e32 v[10:11], 0
	v_mov_b64_e32 v[12:13], 0
	v_mov_b64_e32 v[14:15], 0
	v_mov_b64_e32 v[16:17], 0
	v_mov_b64_e32 v[18:19], 0
	v_mov_b64_e32 v[20:21], 0
	v_mov_b64_e32 v[22:23], 0
	v_mov_b64_e32 v[24:25], 0
	v_mov_b64_e32 v[26:27], 0
	v_mov_b64_e32 v[28:29], 0
	v_mov_b64_e32 v[30:31], 0
	v_mov_b64_e32 v[32:33], 0
	v_mov_b64_e32 v[34:35], 0
	v_mov_b64_e32 v[36:37], 0
	v_mov_b64_e32 v[38:39], 0
	v_mov_b64_e32 v[40:41], 0
	v_mov_b64_e32 v[42:43], 0
	v_mov_b64_e32 v[44:45], 0
	v_mov_b64_e32 v[46:47], 0
	v_mov_b64_e32 v[48:49], 0
	v_mov_b64_e32 v[50:51], 0
	v_mov_b64_e32 v[52:53], 0
	v_mov_b64_e32 v[54:55], 0
	v_mov_b64_e32 v[56:57], 0
	v_mov_b64_e32 v[58:59], 0
	v_mov_b64_e32 v[60:61], 0
	v_mov_b64_e32 v[62:63], 0
	v_mov_b64_e32 v[64:65], 0
	v_mov_b64_e32 v[66:67], 0
	v_mov_b64_e32 v[68:69], 0
	v_mov_b64_e32 v[70:71], 0
	v_mov_b64_e32 v[72:73], 0
	v_mov_b64_e32 v[74:75], 0
	v_mov_b64_e32 v[76:77], 0
	v_mov_b64_e32 v[78:79], 0
	v_mov_b64_e32 v[80:81], 0
	v_mov_b64_e32 v[82:83], 0
	v_mov_b64_e32 v[84:85], 0
	v_mov_b64_e32 v[86:87], 0
	v_mov_b64_e32 v[88:89], 0
	v_mov_b64_e32 v[90:91], 0
	v_mov_b64_e32 v[92:93], 0
	v_mov_b64_e32 v[94:95], 0
	v_mov_b64_e32 v[96:97], 0
	v_mov_b64_e32 v[98:99], 0
	v_mov_b64_e32 v[100:101], 0
	v_mov_b64_e32 v[102:103], 0
	v_mov_b64_e32 v[104:105], 0
	v_mov_b64_e32 v[106:107], 0
	v_mov_b64_e32 v[108:109], 0
	v_mov_b64_e32 v[110:111], 0
	v_mov_b64_e32 v[112:113], 0
	v_mov_b64_e32 v[114:115], 0
	v_mov_b64_e32 v[116:117], 0
	v_mov_b64_e32 v[118:119], 0
	v_mov_b64_e32 v[120:121], 0
	v_mov_b64_e32 v[122:123], 0
	v_mov_b64_e32 v[124:125], 0
	v_mov_b64_e32 v[126:127], 0

;     ...
;             const char* a1 = PG8_KADV(cA, (size_t)(t + 1) * kstep);
;             const char* a2 = last ? nA : PG8_KADV(cA, (size_t)(t + 2) * kstep); const char* b2 = last ? nB : PG8_KADV(cB, (size_t)(t + 2) * kstep);
;             const char* a3 = PG8_KADV(a2, kstep); const char* b3 = PG8_KADV(b2, kstep);
;     ...
; #pragma unroll
;         for (int a = 0; a < 2; ++a)
; #pragma unroll
;             for (int b = 0; b < 2; ++b)
; #pragma unroll
;                 for (int m = 0; m < 4; ++m)
; #pragma unroll
;                     for (int n = 0; n < 2; ++n) acc[a][b][m][n] = (f32x4){0.f, 0.f, 0.f, 0.f};
;         cur = nxt; cA = nA; cB = nB; ++ui;
.LBB0_1065:
	s_add_u32 s2, s62, 0xffffff00
	s_addc_u32 s25, s63, -1
	s_mov_b32 s3, -2
	v_mov_b64_e32 v[0:1], 0
	v_mov_b64_e32 v[2:3], 0
	v_mov_b64_e32 v[4:5], 0
	v_mov_b64_e32 v[6:7], 0
	v_mov_b64_e32 v[8:9], 0
	v_mov_b64_e32 v[10:11], 0
	v_mov_b64_e32 v[12:13], 0
	v_mov_b64_e32 v[14:15], 0
	v_mov_b64_e32 v[16:17], 0
	v_mov_b64_e32 v[18:19], 0
	v_mov_b64_e32 v[20:21], 0
	v_mov_b64_e32 v[22:23], 0
	v_mov_b64_e32 v[24:25], 0
	v_mov_b64_e32 v[26:27], 0
	v_mov_b64_e32 v[28:29], 0
	v_mov_b64_e32 v[30:31], 0
	v_mov_b64_e32 v[32:33], 0
	v_mov_b64_e32 v[34:35], 0
	v_mov_b64_e32 v[36:37], 0
	v_mov_b64_e32 v[38:39], 0
	v_mov_b64_e32 v[40:41], 0
	v_mov_b64_e32 v[42:43], 0
	v_mov_b64_e32 v[44:45], 0
	v_mov_b64_e32 v[46:47], 0
	v_mov_b64_e32 v[48:49], 0
	v_mov_b64_e32 v[50:51], 0
	v_mov_b64_e32 v[52:53], 0
	v_mov_b64_e32 v[54:55], 0
	v_mov_b64_e32 v[56:57], 0
	v_mov_b64_e32 v[58:59], 0
	v_mov_b64_e32 v[60:61], 0
	v_mov_b64_e32 v[62:63], 0
	v_mov_b64_e32 v[64:65], 0
	v_mov_b64_e32 v[66:67], 0
	v_mov_b64_e32 v[68:69], 0
	v_mov_b64_e32 v[70:71], 0
	v_mov_b64_e32 v[72:73], 0
	v_mov_b64_e32 v[74:75], 0
	v_mov_b64_e32 v[76:77], 0
	v_mov_b64_e32 v[78:79], 0
	v_mov_b64_e32 v[80:81], 0
	v_mov_b64_e32 v[82:83], 0
	v_mov_b64_e32 v[84:85], 0
	v_mov_b64_e32 v[86:87], 0
	v_mov_b64_e32 v[88:89], 0
	v_mov_b64_e32 v[90:91], 0
	v_mov_b64_e32 v[92:93], 0
	v_mov_b64_e32 v[94:95], 0
	v_mov_b64_e32 v[96:97], 0
	v_mov_b64_e32 v[98:99], 0
	v_mov_b64_e32 v[100:101], 0
	v_mov_b64_e32 v[102:103], 0
	v_mov_b64_e32 v[104:105], 0
	v_mov_b64_e32 v[106:107], 0
	v_mov_b64_e32 v[108:109], 0
	v_mov_b64_e32 v[110:111], 0
	v_mov_b64_e32 v[112:113], 0
	v_mov_b64_e32 v[114:115], 0
	v_mov_b64_e32 v[116:117], 0
	v_mov_b64_e32 v[118:119], 0
	v_mov_b64_e32 v[120:121], 0
	v_mov_b64_e32 v[122:123], 0
	v_mov_b64_e32 v[124:125], 0
	v_mov_b64_e32 v[126:127], 0
